# v15 + static-ticket item heads skip the store-drain wait (only the dynamic pop needs vmcnt 0)
# speedup vs baseline: 1.0025x; 1.0007x over previous
; __device__ __forceinline__ void phase_attn(const Params& p, LAS unsigned char* lds, unsigned* queue) {
;     ...
;         if (tid == 0) *tick = __hip_atomic_fetch_add(queue, 1u, __ATOMIC_RELAXED, __HIP_MEMORY_SCOPE_AGENT);
;         __syncthreads();
;         const int idx = (int)*tick;
.LBB0_333:
	s_and_saveexec_b64 s[4:5], s[92:93]
	s_cbranch_execz .LBB0_337
	s_mov_b64 s[8:9], exec
	v_mbcnt_lo_u32_b32 v2, s8, 0
	v_mbcnt_hi_u32_b32 v2, s9, v2
	v_cmp_eq_u32_e32 vcc, 0, v2
	s_and_saveexec_b64 s[6:7], vcc
	s_cbranch_execz .LBB0_336
	v_readfirstlane_b32 s98, v251
	s_cmpk_gt_i32 s2, 0x7f
	s_cbranch_scc0 .Lq_dyn
	s_cmp_eq_u32 s98, 1
	s_cbranch_scc0 .Lq_try2
	s_sub_i32 s0, s2, 0x80
	v_mov_b32_e32 v251, 2
	v_mov_b32_e32 v4, s0
	s_or_b64 exec, exec, s[6:7]
	s_branch .Lq_nowait
.Lq_try2:
	s_cmp_eq_u32 s98, 2
	s_cbranch_scc0 .Lq_dyn
	s_add_i32 s0, s2, 64
	s_and_b32 s0, s0, 0x7f
	s_add_i32 s0, s0, 0x80
	v_mov_b32_e32 v251, 0
	v_mov_b32_e32 v4, s0
	s_or_b64 exec, exec, s[6:7]
	s_branch .Lq_nowait

; __device__ __forceinline__ void phase_attn(const Params& p, LAS unsigned char* lds, unsigned* queue) {
;     ...
;         if (tid == 0) *tick = __hip_atomic_fetch_add(queue, 1u, __ATOMIC_RELAXED, __HIP_MEMORY_SCOPE_AGENT);
;         __syncthreads();
;         const int idx = (int)*tick;
.Lq_nowait:
	v_readfirstlane_b32 s0, v4
	v_mov_b32_e32 v4, s90
	s_nop 0
	v_add_u32_e32 v2, s0, v2
	ds_write_b32 v4, v2
